# FFN hidden buffer moved to the SC region (ws+315 MiB) so PA/PB no longer overlay it; P4|P5 barrier XCD-local as well
# speedup vs baseline: 1.0162x; 1.0130x over previous
; __device__ __forceinline__ unsigned pk2(float lo, float hi) { const f32x2c v = {lo, hi}; const bf16x2c b = __builtin_convertvector(v, bf16x2c); return __builtin_bit_cast(unsigned, b); }
; __device__ __forceinline__ float silu_f(float x) { return x * fast_sigmoid(x); }
;     __device__ __forceinline__ void operator()(const f32x4 (&acc)[2][2][4][2], const pg8::Unit& u, int wr, int wc, int fr, int fq) const {
;         const int row0 = u.pm * 256 + wr * 64 + fr, col0 = u.pn * 128 + wc * 32 + 8 * fq;
; #pragma unroll
;         for (int ai = 0; ai < 2; ++ai)
; #pragma unroll
;             for (int m = 0; m < 4; ++m) {
;                 bf16_t* rowp = O + (size_t)(row0 + ai * 128 + m * 16) * ldc + col0;
;                 const f32x4 a0 = acc[ai][0][m][0], a1 = acc[ai][0][m][1], b0 = acc[ai][1][m][0], b1 = acc[ai][1][m][1];
;                 u32x4 w;
;                 w.x = pk2(silu_f(a0[0]) * b0[0], silu_f(a0[1]) * b0[1]); w.y = pk2(silu_f(a0[2]) * b0[2], silu_f(a0[3]) * b0[3]);
;                 w.z = pk2(silu_f(a1[0]) * b1[0], silu_f(a1[1]) * b1[1]); w.w = pk2(silu_f(a1[2]) * b1[2], silu_f(a1[3]) * b1[3]);
;                 *(u32x4*)rowp = w;
;             }
.LBB0_153:
	v_mul_f32_e32 v155, 0xbfb8aa3b, v124
	v_exp_f32_e32 v155, v155
	v_mul_f32_e32 v158, 0xbfb8aa3b, v125
	v_exp_f32_e32 v159, v158
	v_lshl_add_u32 v154, s28, 8, v148
	v_add_f32_e32 v155, 1.0, v155
	v_rcp_f32_e32 v158, v155
	v_add_f32_e32 v155, 1.0, v159
	v_mul_f32_e32 v159, 0xbfb8aa3b, v126
	v_exp_f32_e32 v160, v159
	v_mul_f32_e32 v159, 0xbfb8aa3b, v127
	v_exp_f32_e32 v161, v159
	v_rcp_f32_e32 v159, v155
	v_add_f32_e32 v155, 1.0, v160
	v_rcp_f32_e32 v160, v155
	v_add_f32_e32 v155, 1.0, v161
	v_rcp_f32_e32 v161, v155
	v_pk_mul_f32 v[124:125], v[124:125], v[158:159]
	v_lshl_add_u32 v144, s71, 7, v150
	v_pk_mul_f32 v[120:121], v[124:125], v[120:121]
	v_pk_mul_f32 v[124:125], v[126:127], v[160:161]
	v_cvt_pk_bf16_f32 v120, v120, v121
	v_mul_f32_e32 v121, 0xbfb8aa3b, v116
	v_pk_mul_f32 v[122:123], v[124:125], v[122:123]
	v_exp_f32_e32 v124, v121
	v_mul_f32_e32 v121, 0xbfb8aa3b, v117
	v_exp_f32_e32 v125, v121
	v_cvt_pk_bf16_f32 v121, v122, v123
	v_add_f32_e32 v122, 1.0, v124
	v_mul_f32_e32 v124, 0xbfb8aa3b, v118
	v_add_f32_e32 v123, 1.0, v125
	v_mul_f32_e32 v125, 0xbfb8aa3b, v119
	v_exp_f32_e32 v124, v124
	v_exp_f32_e32 v125, v125
	v_rcp_f32_e32 v122, v122
	v_rcp_f32_e32 v123, v123
	v_add_f32_e32 v124, 1.0, v124
	v_add_f32_e32 v125, 1.0, v125
	v_rcp_f32_e32 v124, v124
	v_rcp_f32_e32 v125, v125
	v_pk_mul_f32 v[116:117], v[116:117], v[122:123]
	v_ashrrev_i32_e32 v145, 31, v144
	v_pk_mul_f32 v[112:113], v[116:117], v[112:113]
	v_mul_f32_e32 v116, 0xbfb8aa3b, v110
	v_cvt_pk_bf16_f32 v122, v112, v113
	v_pk_mul_f32 v[112:113], v[118:119], v[124:125]
	v_mul_f32_e32 v117, 0xbfb8aa3b, v111
	v_pk_mul_f32 v[112:113], v[112:113], v[114:115]
	v_mul_f32_e32 v114, 0xbfb8aa3b, v108
	v_mul_f32_e32 v115, 0xbfb8aa3b, v109
	v_exp_f32_e32 v114, v114
	v_exp_f32_e32 v115, v115
	v_exp_f32_e32 v116, v116
	v_exp_f32_e32 v117, v117
	v_add_f32_e32 v114, 1.0, v114
	v_add_f32_e32 v115, 1.0, v115
	v_rcp_f32_e32 v114, v114
	v_rcp_f32_e32 v115, v115
	v_add_f32_e32 v116, 1.0, v116
	v_add_f32_e32 v117, 1.0, v117
	v_rcp_f32_e32 v116, v116
	v_rcp_f32_e32 v117, v117
	v_pk_mul_f32 v[108:109], v[108:109], v[114:115]
	s_cselect_b32 s98, 1, 0
	s_add_u32 s100, s96, 0xd000000
	s_addc_u32 s101, s97, 0
	s_cmp_lg_u32 s98, 0
	v_mov_b64_e32 v[146:147], s[100:101]
	v_pk_mul_f32 v[104:105], v[108:109], v[104:105]
	v_pk_mul_f32 v[108:109], v[110:111], v[116:117]
	v_cvt_pk_bf16_f32 v104, v104, v105
	v_mul_f32_e32 v105, 0xbfb8aa3b, v100
	v_pk_mul_f32 v[106:107], v[108:109], v[106:107]
	v_exp_f32_e32 v108, v105
	v_mul_f32_e32 v105, 0xbfb8aa3b, v101
	v_exp_f32_e32 v109, v105
	v_cvt_pk_bf16_f32 v105, v106, v107
	v_add_f32_e32 v106, 1.0, v108
	v_mul_f32_e32 v108, 0xbfb8aa3b, v102
	v_add_f32_e32 v107, 1.0, v109
	v_mul_f32_e32 v109, 0xbfb8aa3b, v103
	v_exp_f32_e32 v108, v108
	v_exp_f32_e32 v109, v109
	v_rcp_f32_e32 v106, v106
	v_rcp_f32_e32 v107, v107
	v_add_f32_e32 v108, 1.0, v108
	v_add_f32_e32 v109, 1.0, v109
	v_rcp_f32_e32 v108, v108
	v_rcp_f32_e32 v109, v109
	v_pk_mul_f32 v[100:101], v[100:101], v[106:107]
	v_cvt_pk_bf16_f32 v123, v112, v113
	v_pk_mul_f32 v[96:97], v[100:101], v[96:97]
	v_mul_f32_e32 v100, 0xbfb8aa3b, v94
	v_cvt_pk_bf16_f32 v106, v96, v97
	v_pk_mul_f32 v[96:97], v[102:103], v[108:109]
	v_mul_f32_e32 v101, 0xbfb8aa3b, v95
	v_pk_mul_f32 v[96:97], v[96:97], v[98:99]
	v_mul_f32_e32 v98, 0xbfb8aa3b, v92
	v_mul_f32_e32 v99, 0xbfb8aa3b, v93
	v_exp_f32_e32 v98, v98
	v_exp_f32_e32 v99, v99
	v_exp_f32_e32 v100, v100
	v_exp_f32_e32 v101, v101
	v_add_f32_e32 v98, 1.0, v98
	v_add_f32_e32 v99, 1.0, v99
	v_rcp_f32_e32 v98, v98
	v_rcp_f32_e32 v99, v99
	v_add_f32_e32 v100, 1.0, v100
	v_add_f32_e32 v101, 1.0, v101
	v_rcp_f32_e32 v100, v100
	v_rcp_f32_e32 v101, v101
	v_pk_mul_f32 v[92:93], v[92:93], v[98:99]
	v_or_b32_e32 v112, 16, v154
	v_pk_mul_f32 v[88:89], v[92:93], v[88:89]
	v_pk_mul_f32 v[92:93], v[94:95], v[100:101]
	v_cvt_pk_bf16_f32 v88, v88, v89
	v_mul_f32_e32 v89, 0xbfb8aa3b, v84
	v_pk_mul_f32 v[90:91], v[92:93], v[90:91]
	v_exp_f32_e32 v92, v89
	v_mul_f32_e32 v89, 0xbfb8aa3b, v85
	v_exp_f32_e32 v93, v89
	v_cvt_pk_bf16_f32 v89, v90, v91
	v_add_f32_e32 v90, 1.0, v92
	v_mul_f32_e32 v92, 0xbfb8aa3b, v86
	v_add_f32_e32 v91, 1.0, v93
	v_mul_f32_e32 v93, 0xbfb8aa3b, v87
	v_exp_f32_e32 v92, v92
	v_exp_f32_e32 v93, v93
	v_rcp_f32_e32 v90, v90
	v_rcp_f32_e32 v91, v91
	v_add_f32_e32 v92, 1.0, v92
	v_add_f32_e32 v93, 1.0, v93
	v_rcp_f32_e32 v92, v92
	v_rcp_f32_e32 v93, v93
	v_pk_mul_f32 v[84:85], v[84:85], v[90:91]
	v_cvt_pk_bf16_f32 v107, v96, v97
	v_pk_mul_f32 v[80:81], v[84:85], v[80:81]
	v_mul_f32_e32 v84, 0xbfb8aa3b, v78
	v_cvt_pk_bf16_f32 v90, v80, v81
	v_pk_mul_f32 v[80:81], v[86:87], v[92:93]
	v_mul_f32_e32 v85, 0xbfb8aa3b, v79
	v_pk_mul_f32 v[80:81], v[80:81], v[82:83]
	v_mul_f32_e32 v82, 0xbfb8aa3b, v76
	v_mul_f32_e32 v83, 0xbfb8aa3b, v77
	v_exp_f32_e32 v82, v82
	v_exp_f32_e32 v83, v83
	v_exp_f32_e32 v84, v84
	v_exp_f32_e32 v85, v85
	v_add_f32_e32 v82, 1.0, v82
	v_add_f32_e32 v83, 1.0, v83
	v_rcp_f32_e32 v82, v82
	v_rcp_f32_e32 v83, v83
	v_add_f32_e32 v84, 1.0, v84
	v_add_f32_e32 v85, 1.0, v85
	v_rcp_f32_e32 v84, v84
	v_rcp_f32_e32 v85, v85
	v_pk_mul_f32 v[76:77], v[76:77], v[82:83]
	v_or_b32_e32 v96, 32, v154
	v_pk_mul_f32 v[72:73], v[76:77], v[72:73]
	v_pk_mul_f32 v[76:77], v[78:79], v[84:85]
	v_cvt_pk_bf16_f32 v72, v72, v73
	v_mul_f32_e32 v73, 0xbfb8aa3b, v68
	v_pk_mul_f32 v[74:75], v[76:77], v[74:75]
	v_exp_f32_e32 v76, v73
	v_mul_f32_e32 v73, 0xbfb8aa3b, v69
	v_exp_f32_e32 v77, v73
	v_cvt_pk_bf16_f32 v73, v74, v75
	v_add_f32_e32 v74, 1.0, v76
	v_mul_f32_e32 v76, 0xbfb8aa3b, v70
	v_add_f32_e32 v75, 1.0, v77
	v_mul_f32_e32 v77, 0xbfb8aa3b, v71
	v_exp_f32_e32 v76, v76
; __device__ __forceinline__ unsigned pk2(float lo, float hi) { const f32x2c v = {lo, hi}; const bf16x2c b = __builtin_convertvector(v, bf16x2c); return __builtin_bit_cast(unsigned, b); }
; __device__ __forceinline__ float silu_f(float x) { return x * fast_sigmoid(x); }
;     __device__ __forceinline__ void operator()(const f32x4 (&acc)[2][2][4][2], const pg8::Unit& u, int wr, int wc, int fr, int fq) const {
;         const int row0 = u.pm * 256 + wr * 64 + fr, col0 = u.pn * 128 + wc * 32 + 8 * fq;
; #pragma unroll
;         for (int ai = 0; ai < 2; ++ai)
; #pragma unroll
;             for (int m = 0; m < 4; ++m) {
;                 bf16_t* rowp = O + (size_t)(row0 + ai * 128 + m * 16) * ldc + col0;
;                 const f32x4 a0 = acc[ai][0][m][0], a1 = acc[ai][0][m][1], b0 = acc[ai][1][m][0], b1 = acc[ai][1][m][1];
;                 u32x4 w;
;                 w.x = pk2(silu_f(a0[0]) * b0[0], silu_f(a0[1]) * b0[1]); w.y = pk2(silu_f(a0[2]) * b0[2], silu_f(a0[3]) * b0[3]);
;                 w.z = pk2(silu_f(a1[0]) * b1[0], silu_f(a1[1]) * b1[1]); w.w = pk2(silu_f(a1[2]) * b1[2], silu_f(a1[3]) * b1[3]);
;                 *(u32x4*)rowp = w;
;             }
	v_exp_f32_e32 v77, v77
	v_rcp_f32_e32 v74, v74
	v_rcp_f32_e32 v75, v75
	v_add_f32_e32 v76, 1.0, v76
	v_add_f32_e32 v77, 1.0, v77
	v_rcp_f32_e32 v76, v76
	v_rcp_f32_e32 v77, v77
	v_pk_mul_f32 v[68:69], v[68:69], v[74:75]
	v_cvt_pk_bf16_f32 v91, v80, v81
	v_pk_mul_f32 v[64:65], v[68:69], v[64:65]
	v_mul_f32_e32 v68, 0xbfb8aa3b, v62
	v_cvt_pk_bf16_f32 v74, v64, v65
	v_pk_mul_f32 v[64:65], v[70:71], v[76:77]
	v_mul_f32_e32 v69, 0xbfb8aa3b, v63
	v_pk_mul_f32 v[64:65], v[64:65], v[66:67]
	v_mul_f32_e32 v66, 0xbfb8aa3b, v60
	v_mul_f32_e32 v67, 0xbfb8aa3b, v61
	v_exp_f32_e32 v66, v66
	v_exp_f32_e32 v67, v67
	v_exp_f32_e32 v68, v68
	v_exp_f32_e32 v69, v69
	v_add_f32_e32 v66, 1.0, v66
	v_add_f32_e32 v67, 1.0, v67
	v_rcp_f32_e32 v66, v66
	v_rcp_f32_e32 v67, v67
	v_add_f32_e32 v68, 1.0, v68
	v_add_f32_e32 v69, 1.0, v69
	v_rcp_f32_e32 v68, v68
	v_rcp_f32_e32 v69, v69
	v_pk_mul_f32 v[60:61], v[60:61], v[66:67]
	v_or_b32_e32 v80, 48, v154
	v_pk_mul_f32 v[56:57], v[60:61], v[56:57]
	v_pk_mul_f32 v[60:61], v[62:63], v[68:69]
	v_cvt_pk_bf16_f32 v56, v56, v57
	v_mul_f32_e32 v57, 0xbfb8aa3b, v52
	v_pk_mul_f32 v[58:59], v[60:61], v[58:59]
	v_exp_f32_e32 v60, v57
	v_mul_f32_e32 v57, 0xbfb8aa3b, v53
	v_exp_f32_e32 v61, v57
	v_cvt_pk_bf16_f32 v57, v58, v59
	v_add_f32_e32 v58, 1.0, v60
	v_mul_f32_e32 v60, 0xbfb8aa3b, v54
	v_add_f32_e32 v59, 1.0, v61
	v_mul_f32_e32 v61, 0xbfb8aa3b, v55
	v_exp_f32_e32 v60, v60
	v_exp_f32_e32 v61, v61
	v_rcp_f32_e32 v58, v58
	v_rcp_f32_e32 v59, v59
	v_add_f32_e32 v60, 1.0, v60
	v_add_f32_e32 v61, 1.0, v61
	v_rcp_f32_e32 v60, v60
	v_rcp_f32_e32 v61, v61
	v_pk_mul_f32 v[52:53], v[52:53], v[58:59]
	v_cvt_pk_bf16_f32 v75, v64, v65
	v_pk_mul_f32 v[48:49], v[52:53], v[48:49]
	v_mul_f32_e32 v52, 0xbfb8aa3b, v46
	v_cvt_pk_bf16_f32 v58, v48, v49
	v_pk_mul_f32 v[48:49], v[54:55], v[60:61]
	v_mul_f32_e32 v53, 0xbfb8aa3b, v47
	v_pk_mul_f32 v[48:49], v[48:49], v[50:51]
	v_mul_f32_e32 v50, 0xbfb8aa3b, v44
	v_mul_f32_e32 v51, 0xbfb8aa3b, v45
	v_exp_f32_e32 v50, v50
	v_exp_f32_e32 v51, v51
	v_exp_f32_e32 v52, v52
	v_exp_f32_e32 v53, v53
	v_add_f32_e32 v50, 1.0, v50
	v_add_f32_e32 v51, 1.0, v51
	v_rcp_f32_e32 v50, v50
	v_rcp_f32_e32 v51, v51
	v_add_f32_e32 v52, 1.0, v52
	v_add_f32_e32 v53, 1.0, v53
	v_rcp_f32_e32 v52, v52
	v_rcp_f32_e32 v53, v53
	v_pk_mul_f32 v[44:45], v[44:45], v[50:51]
	v_add_u32_e32 v64, 0x80, v154
	v_pk_mul_f32 v[40:41], v[44:45], v[40:41]
	v_pk_mul_f32 v[44:45], v[46:47], v[52:53]
	v_cvt_pk_bf16_f32 v40, v40, v41
	v_mul_f32_e32 v41, 0xbfb8aa3b, v36
	v_pk_mul_f32 v[42:43], v[44:45], v[42:43]
	v_exp_f32_e32 v44, v41
	v_mul_f32_e32 v41, 0xbfb8aa3b, v37
	v_exp_f32_e32 v45, v41
	v_cvt_pk_bf16_f32 v41, v42, v43
	v_add_f32_e32 v42, 1.0, v44
	v_mul_f32_e32 v44, 0xbfb8aa3b, v38
	v_add_f32_e32 v43, 1.0, v45
	v_mul_f32_e32 v45, 0xbfb8aa3b, v39
	v_exp_f32_e32 v44, v44
	v_exp_f32_e32 v45, v45
	v_rcp_f32_e32 v42, v42
	v_rcp_f32_e32 v43, v43
	v_add_f32_e32 v44, 1.0, v44
	v_add_f32_e32 v45, 1.0, v45
	v_rcp_f32_e32 v44, v44
	v_rcp_f32_e32 v45, v45
	v_pk_mul_f32 v[36:37], v[36:37], v[42:43]
	v_cvt_pk_bf16_f32 v59, v48, v49
	v_pk_mul_f32 v[32:33], v[36:37], v[32:33]
	v_mul_f32_e32 v36, 0xbfb8aa3b, v30
	v_cvt_pk_bf16_f32 v42, v32, v33
	v_pk_mul_f32 v[32:33], v[38:39], v[44:45]
	v_mul_f32_e32 v37, 0xbfb8aa3b, v31
	v_pk_mul_f32 v[32:33], v[32:33], v[34:35]
	v_mul_f32_e32 v34, 0xbfb8aa3b, v28
	v_mul_f32_e32 v35, 0xbfb8aa3b, v29
	v_exp_f32_e32 v34, v34
	v_exp_f32_e32 v35, v35
	v_exp_f32_e32 v36, v36
	v_exp_f32_e32 v37, v37
	v_add_f32_e32 v34, 1.0, v34
	v_add_f32_e32 v35, 1.0, v35
	v_rcp_f32_e32 v34, v34
	v_rcp_f32_e32 v35, v35
	v_add_f32_e32 v36, 1.0, v36
	v_add_f32_e32 v37, 1.0, v37
	v_rcp_f32_e32 v36, v36
	v_rcp_f32_e32 v37, v37
	v_pk_mul_f32 v[28:29], v[28:29], v[34:35]
	v_add_u32_e32 v48, 0x90, v154
; __device__ __forceinline__ unsigned pk2(float lo, float hi) { const f32x2c v = {lo, hi}; const bf16x2c b = __builtin_convertvector(v, bf16x2c); return __builtin_bit_cast(unsigned, b); }
; __device__ __forceinline__ float silu_f(float x) { return x * fast_sigmoid(x); }
; template <class Epi, class Sched, bool ALIGN_EPI = false, bool SP2 = false>
; __device__ __forceinline__ void gemm_phase(PG8_LAS unsigned char* lds, const Gemm g, const Sched& S, const Epi& E, const int wid) {
;     ...
;         if constexpr (!Epi::AFTER_DRAIN) { E(acc, cur, wr, wc, fr, fq); S.done(cur); }
;         if (!has_next) break;
;     __device__ __forceinline__ void operator()(const f32x4 (&acc)[2][2][4][2], const pg8::Unit& u, int wr, int wc, int fr, int fq) const {
;         const int row0 = u.pm * 256 + wr * 64 + fr, col0 = u.pn * 128 + wc * 32 + 8 * fq;
; #pragma unroll
;         for (int ai = 0; ai < 2; ++ai)
; #pragma unroll
;             for (int m = 0; m < 4; ++m) {
;                 bf16_t* rowp = O + (size_t)(row0 + ai * 128 + m * 16) * ldc + col0;
;                 const f32x4 a0 = acc[ai][0][m][0], a1 = acc[ai][0][m][1], b0 = acc[ai][1][m][0], b1 = acc[ai][1][m][1];
;                 u32x4 w;
;                 w.x = pk2(silu_f(a0[0]) * b0[0], silu_f(a0[1]) * b0[1]); w.y = pk2(silu_f(a0[2]) * b0[2], silu_f(a0[3]) * b0[3]);
;                 w.z = pk2(silu_f(a1[0]) * b1[0], silu_f(a1[1]) * b1[1]); w.w = pk2(silu_f(a1[2]) * b1[2], silu_f(a1[3]) * b1[3]);
;                 *(u32x4*)rowp = w;
;             }
	v_pk_mul_f32 v[24:25], v[28:29], v[24:25]
	v_pk_mul_f32 v[28:29], v[30:31], v[36:37]
	v_cvt_pk_bf16_f32 v24, v24, v25
	v_mul_f32_e32 v25, 0xbfb8aa3b, v20
	v_pk_mul_f32 v[26:27], v[28:29], v[26:27]
	v_exp_f32_e32 v28, v25
	v_mul_f32_e32 v25, 0xbfb8aa3b, v21
	v_exp_f32_e32 v29, v25
	v_cvt_pk_bf16_f32 v25, v26, v27
	v_add_f32_e32 v26, 1.0, v28
	v_mul_f32_e32 v28, 0xbfb8aa3b, v22
	v_add_f32_e32 v27, 1.0, v29
	v_mul_f32_e32 v29, 0xbfb8aa3b, v23
	v_exp_f32_e32 v28, v28
	v_exp_f32_e32 v29, v29
	v_rcp_f32_e32 v26, v26
	v_rcp_f32_e32 v27, v27
	v_add_f32_e32 v28, 1.0, v28
	v_add_f32_e32 v29, 1.0, v29
	v_rcp_f32_e32 v28, v28
	v_rcp_f32_e32 v29, v29
	v_pk_mul_f32 v[20:21], v[20:21], v[26:27]
	v_cvt_pk_bf16_f32 v43, v32, v33
	v_pk_mul_f32 v[16:17], v[20:21], v[16:17]
	v_mul_f32_e32 v20, 0xbfb8aa3b, v14
	v_cvt_pk_bf16_f32 v26, v16, v17
	v_pk_mul_f32 v[16:17], v[22:23], v[28:29]
	v_mul_f32_e32 v21, 0xbfb8aa3b, v15
	v_pk_mul_f32 v[16:17], v[16:17], v[18:19]
	v_mul_f32_e32 v18, 0xbfb8aa3b, v12
	v_mul_f32_e32 v19, 0xbfb8aa3b, v13
	v_exp_f32_e32 v18, v18
	v_exp_f32_e32 v19, v19
	v_exp_f32_e32 v20, v20
	v_exp_f32_e32 v21, v21
	v_add_f32_e32 v18, 1.0, v18
	v_add_f32_e32 v19, 1.0, v19
	v_rcp_f32_e32 v18, v18
	v_rcp_f32_e32 v19, v19
	v_add_f32_e32 v20, 1.0, v20
	v_add_f32_e32 v21, 1.0, v21
	v_rcp_f32_e32 v20, v20
	v_rcp_f32_e32 v21, v21
	v_pk_mul_f32 v[12:13], v[12:13], v[18:19]
	v_add_u32_e32 v32, 0xa0, v154
	v_pk_mul_f32 v[8:9], v[12:13], v[8:9]
	v_pk_mul_f32 v[12:13], v[14:15], v[20:21]
	v_cvt_pk_bf16_f32 v8, v8, v9
	v_mul_f32_e32 v9, 0xbfb8aa3b, v4
	v_pk_mul_f32 v[10:11], v[12:13], v[10:11]
	v_exp_f32_e32 v12, v9
	v_mul_f32_e32 v9, 0xbfb8aa3b, v5
	v_exp_f32_e32 v13, v9
	v_cvt_pk_bf16_f32 v9, v10, v11
	v_add_f32_e32 v10, 1.0, v12
	v_mul_f32_e32 v12, 0xbfb8aa3b, v6
	v_add_f32_e32 v11, 1.0, v13
	v_mul_f32_e32 v13, 0xbfb8aa3b, v7
	v_exp_f32_e32 v12, v12
	v_exp_f32_e32 v13, v13
	v_rcp_f32_e32 v10, v10
	v_rcp_f32_e32 v11, v11
	v_add_f32_e32 v12, 1.0, v12
	v_add_f32_e32 v13, 1.0, v13
	v_rcp_f32_e32 v12, v12
	v_rcp_f32_e32 v13, v13
	v_pk_mul_f32 v[4:5], v[4:5], v[10:11]
	v_cvt_pk_bf16_f32 v27, v16, v17
	v_pk_mul_f32 v[0:1], v[4:5], v[0:1]
	v_add_u32_e32 v16, 0xb0, v154
	v_cvt_pk_bf16_f32 v10, v0, v1
	v_pk_mul_f32 v[0:1], v[6:7], v[12:13]
	v_mad_i64_i32 v[156:157], s[30:31], v154, s70, v[146:147]
	v_lshlrev_b64 v[144:145], 1, v[144:145]
	v_mad_i64_i32 v[112:113], s[30:31], v112, s70, v[146:147]
	v_mad_i64_i32 v[96:97], s[30:31], v96, s70, v[146:147]
	v_mad_i64_i32 v[80:81], s[30:31], v80, s70, v[146:147]
	v_mad_i64_i32 v[64:65], s[30:31], v64, s70, v[146:147]
	v_mad_i64_i32 v[48:49], s[30:31], v48, s70, v[146:147]
	v_mad_i64_i32 v[32:33], s[30:31], v32, s70, v[146:147]
	v_mad_i64_i32 v[16:17], s[30:31], v16, s70, v[146:147]
	v_pk_mul_f32 v[0:1], v[0:1], v[2:3]
	v_lshl_add_u64 v[156:157], v[156:157], 0, v[144:145]
	v_lshl_add_u64 v[112:113], v[112:113], 0, v[144:145]
	v_lshl_add_u64 v[96:97], v[96:97], 0, v[144:145]
	v_lshl_add_u64 v[80:81], v[80:81], 0, v[144:145]
	v_lshl_add_u64 v[64:65], v[64:65], 0, v[144:145]
	v_lshl_add_u64 v[48:49], v[48:49], 0, v[144:145]
	v_lshl_add_u64 v[32:33], v[32:33], 0, v[144:145]
	v_lshl_add_u64 v[16:17], v[16:17], 0, v[144:145]
	v_cvt_pk_bf16_f32 v11, v0, v1
	s_andn2_b64 vcc, exec, s[4:5]
	s_mov_b64 s[4:5], -1
	global_store_dwordx4 v[156:157], v[120:123], off
	global_store_dwordx4 v[112:113], v[104:107], off
	global_store_dwordx4 v[96:97], v[88:91], off
	global_store_dwordx4 v[80:81], v[72:75], off
	global_store_dwordx4 v[64:65], v[56:59], off
	global_store_dwordx4 v[48:49], v[40:43], off
	global_store_dwordx4 v[32:33], v[24:27], off
	global_store_dwordx4 v[16:17], v[8:11], off
	s_cbranch_vccnz .LBB0_146
	s_andn2_b64 vcc, exec, s[6:7]
	s_cbranch_vccnz .LBB0_145
	s_barrier
	s_branch .LBB0_145

; #define PG8_STAGE(bufoff, gbase, voff) do { _Pragma("unroll") for (int _i = 0; _i < 2; ++_i) \
;         __builtin_amdgcn_global_load_lds((const unsigned*)((const char*)(gbase) + (voff)[_i]), (PG8_LAS unsigned*)(lds + (bufoff) + ldsw + _i * 8192), 16, 0, 0); } while (0)
; #define PG8_WAIT_V(n) asm volatile("s_waitcnt vmcnt(" #n ")" ::: "memory")
; #define PG8_BAR __builtin_amdgcn_s_barrier()
; template <class Epi, class Sched, bool ALIGN_EPI = false, bool SP2 = false>
; __device__ __forceinline__ void gemm_phase(PG8_LAS unsigned char* lds, const Gemm g, const Sched& S, const Epi& E, const int wid) {
;     ...
;     for (int i = 0; i < 2; ++i) { int R, C; stage_rc(tid * 16 + i * 8192, R, C); const int Rb = Epi::PERM ? ((R & ~31) + perm32(R & 31)) : R;
;         voffA[i] = (unsigned)(R * K + C) * 2u; voffB[i] = (unsigned)(Rb * K + C) * 2u; }
;     const size_t kstep = (size_t)(BK * 2);
;     const size_t hstep = (size_t)HALF * K * 2;
;     const size_t tstep = 2 * hstep;
;     const unsigned ldsw = (unsigned)wid * 1024u;
;     const int aoff = lds_byte(wr * 64 + fr, fq * 8), boff = lds_byte(wc * 32 + fr, fq * 8);
;     ...
;     const char* cA = (const char*)g.A + (size_t)cur.pm * tstep; const char* cB = (const char*)g.Bt + (size_t)cur.pn * tstep;
;     S.a_ready(cur);
;     if constexpr (SP2) {
;         PG8_STAGE(PG8_SB(0, 0), cB, voffB); PG8_STAGE(PG8_SB(0, 1), cB + hstep, voffB); PG8_STAGE(PG8_SA(0, 0), cA, voffA); PG8_STAGE(PG8_SA(0, 1), cA + hstep, voffA);
;         if (wr == 1) PG8_BAR;
;         PG8_WAIT_V(2); PG8_BAR;
;         PG8_STAGE(PG8_SB(1, 0), cB + kstep, voffB); PG8_STAGE(PG8_SA(1, 0), cA + kstep, voffA); PG8_STAGE(PG8_SB(1, 1), cB + hstep + kstep, voffB);
.LBB0_216:
	v_lshl_add_u32 v0, v13, 4, s33
	v_ashrrev_i32_e32 v1, 31, v0
	v_lshrrev_b32_e32 v1, 22, v1
	v_add_u32_e32 v1, v0, v1
	v_ashrrev_i32_e32 v8, 10, v1
	v_mul_i32_i24_e32 v1, 0x400, v8
	v_sub_u32_e32 v1, v0, v1
	v_lshrrev_b32_e32 v2, 4, v1
	v_bitop3_b32 v1, v2, v1, 32 bitop3:0x6c
	v_ashrrev_i32_e32 v3, 31, v1
	v_lshrrev_b32_e32 v3, 26, v3
	v_lshlrev_b32_e32 v2, 3, v8
	v_add_u32_e32 v3, v1, v3
	v_and_b32_e32 v2, -16, v2
	v_ashrrev_i32_e32 v10, 6, v3
	v_and_b32_e32 v3, 0xc0, v3
	v_add_u32_e32 v2, v10, v2
	v_lshlrev_b32_e32 v4, 5, v8
	v_sub_u32_e32 v1, v1, v3
	v_mov_b32_e32 v3, 1
	s_ashr_i32 s5, s7, 3
	v_and_b32_e32 v9, 32, v4
	v_ashrrev_i16_sdwa v1, v3, sext(v1) dst_sel:DWORD dst_unused:UNUSED_PAD src0_sel:DWORD src1_sel:BYTE_0
	v_lshlrev_b32_e32 v4, 1, v2
	v_lshrrev_b32_e32 v5, 2, v2
	v_and_b32_e32 v6, 3, v10
	s_mov_b32 s7, 0xffffe0
	v_bfe_i32 v11, v1, 0, 16
	v_and_b32_e32 v4, 24, v4
	v_and_b32_e32 v5, 4, v5
	v_and_or_b32 v6, v2, s7, v6
	s_movk_i32 s4, 0xb00
	v_add_u32_e32 v1, v9, v11
	v_or3_b32 v4, v6, v5, v4
	v_mul_lo_u32 v2, v2, s4
	v_add_lshl_u32 v128, v1, v2, 1
	v_mul_u32_u24_e32 v2, 0xb00, v4
	v_add_u32_e32 v0, 0x2000, v0
	v_add_lshl_u32 v130, v2, v1, 1
	v_ashrrev_i32_e32 v1, 31, v0
	v_lshrrev_b32_e32 v1, 22, v1
	v_add_u32_e32 v1, v0, v1
	v_ashrrev_i32_e32 v12, 10, v1
	v_mul_i32_i24_e32 v1, 0x400, v12
	v_sub_u32_e32 v0, v0, v1
	v_lshrrev_b32_e32 v1, 4, v0
	v_bitop3_b32 v0, v1, v0, 32 bitop3:0x6c
	s_add_u32 s35, s92, 0xc00000
	v_ashrrev_i32_e32 v2, 31, v0
	s_addc_u32 s38, s93, 0
	v_lshrrev_b32_e32 v2, 26, v2
	s_add_i32 s5, s6, s5
	v_lshlrev_b32_e32 v1, 3, v12
	v_add_u32_e32 v2, v0, v2
	s_ashr_i32 s6, s5, 31
	v_and_b32_e32 v1, -16, v1
	v_ashrrev_i32_e32 v14, 6, v2
	v_lshlrev_b32_e32 v4, 5, v12
	s_lshr_b32 s6, s6, 28
	v_add_u32_e32 v1, v14, v1
	v_and_b32_e32 v15, 32, v4
	v_and_b32_e32 v4, 3, v14
	s_add_i32 s6, s5, s6
	v_and_or_b32 v4, v1, s7, v4
	s_ashr_i32 s7, s6, 4
	s_and_b32 s6, s6, -16
	s_sub_i32 s6, s5, s6
	s_bfe_i32 s5, s6, 0x80000
	s_bfe_u32 s5, s5, 0x2000d
	s_add_i32 s10, s6, s5
	v_and_b32_e32 v2, 0xffc0, v2
	s_bfe_i32 s5, s10, 0x80000
	s_and_b32 s10, s10, 0xfc
	v_sub_u32_e32 v0, v0, v2
	s_sub_i32 s6, s6, s10
	v_lshrrev_b16_e32 v2, 7, v0
	s_lshl_b32 s7, s7, 2
	s_sext_i32_i16 s11, s5
	s_sext_i32_i8 s6, s6
	v_and_b32_e32 v2, 1, v2
	s_add_i32 s70, s7, s6
	s_ashr_i32 s6, s11, 2
	v_add_u16_e32 v0, v0, v2
	s_lshr_b32 s5, s11, 2
	s_mul_hi_i32 s7, s6, 0x160000
	s_mul_i32 s6, s6, 0x160000
	v_ashrrev_i16_sdwa v0, v3, sext(v0) dst_sel:DWORD dst_unused:UNUSED_PAD src0_sel:DWORD src1_sel:BYTE_0
	v_lshlrev_b32_e32 v2, 1, v1
	v_lshrrev_b32_e32 v3, 2, v1
	s_add_u32 s26, s35, s6
	v_bfe_i32 v16, v0, 0, 16
	v_and_b32_e32 v2, 24, v2
	v_and_b32_e32 v3, 4, v3
	s_addc_u32 s27, s38, s7
	s_add_i32 s39, s33, 0
	v_add_u32_e32 v0, v15, v16
	v_or3_b32 v2, v4, v3, v2
	v_mul_lo_u32 v1, v1, s4
	s_add_i32 m0, s39, 0x10000
	v_add_lshl_u32 v132, v0, v1, 1
	v_mul_u32_u24_e32 v1, 0xb00, v2
	global_load_lds_dwordx4 v130, s[26:27]
	s_add_i32 m0, s39, 0x12000
	v_add_lshl_u32 v134, v1, v0, 1
	s_add_u32 s6, s26, 0xb0000
	global_load_lds_dwordx4 v134, s[26:27]
	s_addc_u32 s7, s27, 0
	s_add_i32 m0, s39, 0x14000
	s_mul_i32 s16, s70, 0x160000
	global_load_lds_dwordx4 v130, s[6:7]
	s_add_i32 m0, s39, 0x16000
	s_mul_hi_i32 s10, s70, 0x160000
	s_add_u32 s24, s96, s16
	s_addc_u32 s25, s97, s10
	s_add_u32 s24, s24, 0xd000000
	s_addc_u32 s25, s25, 0
	s_add_i32 s40, s39, 0x2000
	global_load_lds_dwordx4 v134, s[6:7]
	s_mov_b32 m0, s39
	s_add_u32 s6, s24, 0xb0000
	global_load_lds_dwordx4 v128, s[24:25]
	s_mov_b32 m0, s40
	s_addc_u32 s7, s25, 0
	s_add_i32 s41, s39, 0x4000
	global_load_lds_dwordx4 v132, s[24:25]
	s_mov_b32 m0, s41
	s_add_i32 s42, s39, 0x6000
	global_load_lds_dwordx4 v128, s[6:7]
	s_mov_b32 m0, s42
	v_mov_b32_e32 v131, 0
	global_load_lds_dwordx4 v132, s[6:7]
	v_readlane_b32 s6, v244, 18
	v_mov_b32_e32 v135, v131
	v_mov_b32_e32 v129, v131
	v_mov_b32_e32 v133, v131
	s_cmp_eq_u32 s6, 1
	s_mov_b32 s43, 0
	v_lshl_add_u64 v[4:5], s[26:27], 0, v[130:131]
	v_lshl_add_u64 v[2:3], s[26:27], 0, v[134:135]
	v_lshl_add_u64 v[0:1], s[24:25], 0, v[128:129]
	s_cselect_b64 s[10:11], -1, 0
	s_cmp_lg_u32 s6, 1
	v_lshl_add_u64 v[6:7], s[24:25], 0, v[132:133]
	s_cbranch_scc1 .LBB0_218
	s_barrier

; template <class Epi, class Sched, bool ALIGN_EPI = false, bool SP2 = false>
; __device__ __forceinline__ void gemm_phase(PG8_LAS unsigned char* lds, const Gemm g, const Sched& S, const Epi& E, const int wid) {
;     ...
;         const bool has_next = S.next(ui + 1, nxt);
;         const char* nA = has_next ? (const char*)g.A + (size_t)nxt.pm * tstep : cA; const char* nB = has_next ? (const char*)g.Bt + (size_t)nxt.pn * tstep : cB;
;         for (int t = 0; t < nt; t += 2) {
;             const bool last = (t == nt - 2);
;             const char* a1 = cA + (size_t)(t + 1) * kstep;
;             const char* a2 = last ? nA : cA + (size_t)(t + 2) * kstep; const char* b2 = last ? nB : cB + (size_t)(t + 2) * kstep;
;             const char* a3 = a2 + kstep; const char* b3 = b2 + kstep;
;             if (last && has_next) S.a_ready(nxt);
.LBB0_227:
	s_nop 0
	v_cndmask_b32_e64 v0, 0, 1, s[4:5]
	v_cmp_ne_u32_e64 s[6:7], 1, v0
	s_andn2_b64 vcc, exec, s[4:5]
	s_mov_b64 s[4:5], s[24:25]
	s_cbranch_vccnz .LBB0_229
	s_mul_i32 s4, s69, 0x160000
	s_mul_hi_i32 s5, s69, 0x160000
	s_add_u32 s4, s96, s4
	s_addc_u32 s5, s97, s5
	s_add_u32 s4, s4, 0xd000000
	s_addc_u32 s5, s5, 0

; __device__ __forceinline__ unsigned xb_ld(unsigned* p)              { return __hip_atomic_load(p, __ATOMIC_RELAXED, __HIP_MEMORY_SCOPE_AGENT); }
; __device__ __forceinline__ unsigned xb_add(unsigned* p, unsigned v) { return __hip_atomic_fetch_add(p, v, __ATOMIC_RELAXED, __HIP_MEMORY_SCOPE_AGENT); }
; #define XB_SPIN(cond, bar) do { unsigned _sp = 0; while (cond) { __builtin_amdgcn_s_sleep(1); \
;     if ((++_sp & 255u) == 0u) { if (xb_ld(&(bar)[XB_TMO])) break; if (_sp > XB_SPIN_CAP) { atomicAdd(&(bar)[XB_TMO], 1u); break; } } } } while (0)
; __device__ __forceinline__ void xcd_barrier(const XcdBarrier& b) {
;     ...
;             else XB_SPIN(xb_ld(&bar[XB_TOPGEN]) == tg, bar);
;             __builtin_amdgcn_fence(__ATOMIC_ACQUIRE, "agent");
;             xb_add(&bar[XB_XGEN(b.x)], 1u);
;             asm volatile("s_waitcnt vmcnt(0)" ::: "memory");
;         } else {
;             XB_SPIN(xb_ld(&bar[XB_XGEN(b.x)]) == gen, bar);
;             __builtin_amdgcn_fence(__ATOMIC_ACQUIRE, "agent");
;             asm volatile("s_waitcnt vmcnt(0)" ::: "memory");
.Lei_a4:
	v_mov_b32_e32 v0, 0x2000
	global_load_dword v0, v0, s[4:5] offset:1024 sc1
	s_add_u32 s16, s4, 0x2400
	s_addc_u32 s17, s5, 0
	s_waitcnt vmcnt(0)
	v_cmp_eq_u32_e32 vcc, v0, v1
	s_and_saveexec_b64 s[8:9], vcc
	s_cbranch_execz .LBB0_342
	s_add_u32 s10, s92, 0xc0200
	s_addc_u32 s11, s93, 0
	s_mov_b32 s30, 1
	s_mov_b64 s[20:21], 0
	v_mov_b32_e32 v0, 0
	s_branch .LBB0_333

; __device__ __forceinline__ int lane_now() { int l; asm volatile("v_mbcnt_lo_u32_b32 %0, -1, 0\n\tv_mbcnt_hi_u32_b32 %0, -1, %0" : "=v"(l)); return l; }
; __device__ __forceinline__ unsigned xb_ld(unsigned* p)              { return __hip_atomic_load(p, __ATOMIC_RELAXED, __HIP_MEMORY_SCOPE_AGENT); }
; __device__ __forceinline__ unsigned xb_add(unsigned* p, unsigned v) { return __hip_atomic_fetch_add(p, v, __ATOMIC_RELAXED, __HIP_MEMORY_SCOPE_AGENT); }
; #define XB_SPIN(cond, bar) do { unsigned _sp = 0; while (cond) { __builtin_amdgcn_s_sleep(1); \
;     if ((++_sp & 255u) == 0u) { if (xb_ld(&(bar)[XB_TMO])) break; if (_sp > XB_SPIN_CAP) { atomicAdd(&(bar)[XB_TMO], 1u); break; } } } } while (0)
; __device__ __forceinline__ void xcd_barrier(const XcdBarrier& b) {
;     asm volatile("s_waitcnt vmcnt(0)" ::: "memory");
;     __syncthreads();
;     if (b.w0 && lane_now() == 0) {
;         unsigned* bar = b.bar;
;         __builtin_amdgcn_s_waitcnt(0);
;         unsigned nloc = b.st[0], nx = b.st[1];
;         if (nloc == 0u) { xcd_barrier_complete(bar, b.x, nloc, nx); b.st[0] = nloc; b.st[1] = nx; }
;         const unsigned old = xb_add(&bar[XB_XSUB(b.x)], 1u);
;         const unsigned gen = old / nloc;
;         if (old + 1u == (gen + 1u) * nloc) {
;             __builtin_amdgcn_fence(__ATOMIC_RELEASE, "agent");
;             asm volatile("s_waitcnt vmcnt(0)" ::: "memory");
;             const unsigned og = xb_add(&bar[XB_TOP], 1u);
;             const unsigned tg = og / nx;
;             if (og + 1u == (tg + 1u) * nx) xb_add(&bar[XB_TOPGEN], 1u);
;             else XB_SPIN(xb_ld(&bar[XB_TOPGEN]) == tg, bar);
;             __builtin_amdgcn_fence(__ATOMIC_ACQUIRE, "agent");
;             xb_add(&bar[XB_XGEN(b.x)], 1u);
;             asm volatile("s_waitcnt vmcnt(0)" ::: "memory");
;         } else {
;             XB_SPIN(xb_ld(&bar[XB_XGEN(b.x)]) == gen, bar);
;             __builtin_amdgcn_fence(__ATOMIC_ACQUIRE, "agent");
;             asm volatile("s_waitcnt vmcnt(0)" ::: "memory");
;         }
.LBB0_339:
	s_or_b64 exec, exec, s[20:21]
	s_xor_b64 s[16:17], s[22:23], -1
	s_and_saveexec_b64 s[20:21], s[16:17]
	s_xor_b64 s[20:21], exec, s[20:21]
	s_cbranch_execz .LBB0_342
	s_mov_b64 s[16:17], exec
	v_mbcnt_lo_u32_b32 v0, s16, 0
	v_mbcnt_hi_u32_b32 v0, s17, v0
	v_cmp_eq_u32_e32 vcc, 0, v0
	s_and_b64 s[20:21], exec, vcc
	s_mov_b64 exec, s[20:21]
	s_cbranch_execz .LBB0_342
	s_bcnt1_i32_b64 s16, s[16:17]
	v_mov_b32_e32 v0, 0
	v_mov_b32_e32 v1, s16
	global_atomic_add v0, v1, s[10:11]
.LBB0_342:
	s_or_b64 exec, exec, s[8:9]
	s_waitcnt vmcnt(0)
	v_readlane_b32 s100, v244, 61
	s_cmp_lg_u32 s100, 0
	s_cbranch_scc1 .Lei_b4
	buffer_inv sc1
	s_waitcnt vmcnt(0)
.Lei_b4:
.LBB0_343:
	s_andn2_saveexec_b64 s[6:7], s[6:7]
	s_cbranch_execz .LBB0_363
	s_mov_b64 s[6:7], exec
	v_readlane_b32 s100, v244, 61
	s_cmp_lg_u32 s100, 0
	s_cbranch_scc1 .LBB0_360
	buffer_wbl2 sc1
	s_waitcnt lgkmcnt(0)
	s_waitcnt vmcnt(0)
	v_mbcnt_lo_u32_b32 v1, s6, 0
	v_mbcnt_hi_u32_b32 v1, s7, v1
	v_cmp_eq_u32_e32 vcc, 0, v1
	s_and_saveexec_b64 s[8:9], vcc
	s_cbranch_execz .LBB0_346
	s_bcnt1_i32_b64 s6, s[6:7]
	v_mov_b32_e32 v2, 0xc3000
	v_mov_b32_e32 v3, s6
	global_atomic_add v2, v2, v3, s[92:93] offset:1024 sc0
.LBB0_346:
	s_or_b64 exec, exec, s[8:9]
	v_cvt_f32_u32_e32 v3, v0
	s_waitcnt vmcnt(0)
	v_readfirstlane_b32 s6, v2
	s_add_u32 s8, s92, 0xc3500
	s_addc_u32 s9, s93, 0
	v_rcp_iflag_f32_e32 v3, v3
	v_add_u32_e32 v1, s6, v1
	v_add_u32_e32 v4, 1, v1
	s_mov_b64 s[10:11], -1
	v_mul_f32_e32 v2, 0x4f7ffffe, v3
	v_cvt_u32_f32_e32 v2, v2
	v_sub_u32_e32 v3, 0, v0
	v_mul_lo_u32 v3, v3, v2
	v_mul_hi_u32 v3, v2, v3
	v_add_u32_e32 v2, v2, v3
	v_mul_hi_u32 v2, v1, v2
	v_mul_lo_u32 v3, v2, v0
	v_sub_u32_e32 v1, v1, v3
	v_add_u32_e32 v5, 1, v2
	v_cmp_ge_u32_e32 vcc, v1, v0
	v_sub_u32_e32 v3, v1, v0
	s_nop 0
	v_cndmask_b32_e32 v2, v2, v5, vcc
	v_cndmask_b32_e32 v1, v1, v3, vcc
	v_add_u32_e32 v3, 1, v2
	v_cmp_ge_u32_e32 vcc, v1, v0
	s_nop 1
	v_cndmask_b32_e32 v2, v2, v3, vcc
	v_mul_lo_u32 v1, v0, v2
	v_add_u32_e32 v0, v1, v0
	v_cmp_ne_u32_e32 vcc, v4, v0
	v_mov_b64_e32 v[0:1], s[8:9]
	s_and_saveexec_b64 s[6:7], vcc
	s_cbranch_execz .LBB0_358
	v_mov_b32_e32 v0, 0
	global_load_dword v1, v0, s[8:9] sc1
	s_mov_b64 s[20:21], 0
	s_waitcnt vmcnt(0)
	v_cmp_eq_u32_e32 vcc, v1, v2
	s_and_saveexec_b64 s[16:17], vcc
	s_cbranch_execz .LBB0_357
	s_add_u32 s10, s92, 0xc0200
	s_addc_u32 s11, s93, 0
	s_mov_b32 s30, 1
	s_branch .LBB0_350

; __device__ __forceinline__ unsigned pk2(float lo, float hi) { const f32x2c v = {lo, hi}; const bf16x2c b = __builtin_convertvector(v, bf16x2c); return __builtin_bit_cast(unsigned, b); }
; __device__ __forceinline__ float silu_f(float x) { return x * fast_sigmoid(x); }
;     __device__ __forceinline__ void operator()(const f32x4 (&acc)[2][2][4][2], const pg8::Unit& u, int wr, int wc, int fr, int fq) const {
;         const int row0 = u.pm * 256 + wr * 64 + fr, col0 = u.pn * 128 + wc * 32 + 8 * fq;
; #pragma unroll
;         for (int ai = 0; ai < 2; ++ai)
; #pragma unroll
;             for (int m = 0; m < 4; ++m) {
;                 bf16_t* rowp = O + (size_t)(row0 + ai * 128 + m * 16) * ldc + col0;
;                 const f32x4 a0 = acc[ai][0][m][0], a1 = acc[ai][0][m][1], b0 = acc[ai][1][m][0], b1 = acc[ai][1][m][1];
;                 u32x4 w;
;                 w.x = pk2(silu_f(a0[0]) * b0[0], silu_f(a0[1]) * b0[1]); w.y = pk2(silu_f(a0[2]) * b0[2], silu_f(a0[3]) * b0[3]);
;                 w.z = pk2(silu_f(a1[0]) * b1[0], silu_f(a1[1]) * b1[1]); w.w = pk2(silu_f(a1[2]) * b1[2], silu_f(a1[3]) * b1[3]);
;                 *(u32x4*)rowp = w;
;             }
.LBB0_1314:
	v_mul_f32_e32 v155, 0xbfb8aa3b, v124
	v_exp_f32_e32 v155, v155
	v_mul_f32_e32 v158, 0xbfb8aa3b, v125
	v_exp_f32_e32 v159, v158
	v_lshl_add_u32 v154, s20, 8, v148
	v_add_f32_e32 v155, 1.0, v155
	v_rcp_f32_e32 v158, v155
	v_add_f32_e32 v155, 1.0, v159
	v_mul_f32_e32 v159, 0xbfb8aa3b, v126
	v_exp_f32_e32 v160, v159
	v_mul_f32_e32 v159, 0xbfb8aa3b, v127
	v_exp_f32_e32 v161, v159
	v_rcp_f32_e32 v159, v155
	v_add_f32_e32 v155, 1.0, v160
	v_rcp_f32_e32 v160, v155
	v_add_f32_e32 v155, 1.0, v161
	v_rcp_f32_e32 v161, v155
	v_pk_mul_f32 v[124:125], v[124:125], v[158:159]
	v_lshl_add_u32 v144, s45, 7, v150
	v_pk_mul_f32 v[120:121], v[124:125], v[120:121]
	v_pk_mul_f32 v[124:125], v[126:127], v[160:161]
	v_cvt_pk_bf16_f32 v120, v120, v121
	v_mul_f32_e32 v121, 0xbfb8aa3b, v116
	v_pk_mul_f32 v[122:123], v[124:125], v[122:123]
	v_exp_f32_e32 v124, v121
	v_mul_f32_e32 v121, 0xbfb8aa3b, v117
	v_exp_f32_e32 v125, v121
	v_cvt_pk_bf16_f32 v121, v122, v123
	v_add_f32_e32 v122, 1.0, v124
	v_mul_f32_e32 v124, 0xbfb8aa3b, v118
	v_add_f32_e32 v123, 1.0, v125
	v_mul_f32_e32 v125, 0xbfb8aa3b, v119
	v_exp_f32_e32 v124, v124
	v_exp_f32_e32 v125, v125
	v_rcp_f32_e32 v122, v122
	v_rcp_f32_e32 v123, v123
	v_add_f32_e32 v124, 1.0, v124
	v_add_f32_e32 v125, 1.0, v125
	v_rcp_f32_e32 v124, v124
	v_rcp_f32_e32 v125, v125
	v_pk_mul_f32 v[116:117], v[116:117], v[122:123]
	v_ashrrev_i32_e32 v145, 31, v144
	v_pk_mul_f32 v[112:113], v[116:117], v[112:113]
	v_mul_f32_e32 v116, 0xbfb8aa3b, v110
	v_cvt_pk_bf16_f32 v122, v112, v113
	v_pk_mul_f32 v[112:113], v[118:119], v[124:125]
	v_mul_f32_e32 v117, 0xbfb8aa3b, v111
	v_pk_mul_f32 v[112:113], v[112:113], v[114:115]
	v_mul_f32_e32 v114, 0xbfb8aa3b, v108
	v_mul_f32_e32 v115, 0xbfb8aa3b, v109
	v_exp_f32_e32 v114, v114
	v_exp_f32_e32 v115, v115
	v_exp_f32_e32 v116, v116
	v_exp_f32_e32 v117, v117
	v_add_f32_e32 v114, 1.0, v114
	v_add_f32_e32 v115, 1.0, v115
	v_rcp_f32_e32 v114, v114
	v_rcp_f32_e32 v115, v115
	v_add_f32_e32 v116, 1.0, v116
	v_add_f32_e32 v117, 1.0, v117
	v_rcp_f32_e32 v116, v116
	v_rcp_f32_e32 v117, v117
	v_pk_mul_f32 v[108:109], v[108:109], v[114:115]
	s_cselect_b32 s98, 1, 0
	s_add_u32 s100, s96, 0xd000000
	s_addc_u32 s101, s97, 0
	s_cmp_lg_u32 s98, 0
	v_mov_b64_e32 v[146:147], s[100:101]
	v_pk_mul_f32 v[104:105], v[108:109], v[104:105]
	v_pk_mul_f32 v[108:109], v[110:111], v[116:117]
	v_cvt_pk_bf16_f32 v104, v104, v105
	v_mul_f32_e32 v105, 0xbfb8aa3b, v100
	v_pk_mul_f32 v[106:107], v[108:109], v[106:107]
	v_exp_f32_e32 v108, v105
	v_mul_f32_e32 v105, 0xbfb8aa3b, v101
	v_exp_f32_e32 v109, v105
	v_cvt_pk_bf16_f32 v105, v106, v107
	v_add_f32_e32 v106, 1.0, v108
	v_mul_f32_e32 v108, 0xbfb8aa3b, v102
	v_add_f32_e32 v107, 1.0, v109
	v_mul_f32_e32 v109, 0xbfb8aa3b, v103
	v_exp_f32_e32 v108, v108
	v_exp_f32_e32 v109, v109
	v_rcp_f32_e32 v106, v106
	v_rcp_f32_e32 v107, v107
	v_add_f32_e32 v108, 1.0, v108
	v_add_f32_e32 v109, 1.0, v109
	v_rcp_f32_e32 v108, v108
	v_rcp_f32_e32 v109, v109
	v_pk_mul_f32 v[100:101], v[100:101], v[106:107]
	v_cvt_pk_bf16_f32 v123, v112, v113
	v_pk_mul_f32 v[96:97], v[100:101], v[96:97]
	v_mul_f32_e32 v100, 0xbfb8aa3b, v94
	v_cvt_pk_bf16_f32 v106, v96, v97
	v_pk_mul_f32 v[96:97], v[102:103], v[108:109]
	v_mul_f32_e32 v101, 0xbfb8aa3b, v95
	v_pk_mul_f32 v[96:97], v[96:97], v[98:99]
	v_mul_f32_e32 v98, 0xbfb8aa3b, v92
	v_mul_f32_e32 v99, 0xbfb8aa3b, v93
	v_exp_f32_e32 v98, v98
	v_exp_f32_e32 v99, v99
	v_exp_f32_e32 v100, v100
	v_exp_f32_e32 v101, v101
	v_add_f32_e32 v98, 1.0, v98
	v_add_f32_e32 v99, 1.0, v99
	v_rcp_f32_e32 v98, v98
	v_rcp_f32_e32 v99, v99
	v_add_f32_e32 v100, 1.0, v100
	v_add_f32_e32 v101, 1.0, v101
	v_rcp_f32_e32 v100, v100
	v_rcp_f32_e32 v101, v101
	v_pk_mul_f32 v[92:93], v[92:93], v[98:99]
	v_or_b32_e32 v112, 16, v154
	v_pk_mul_f32 v[88:89], v[92:93], v[88:89]
	v_pk_mul_f32 v[92:93], v[94:95], v[100:101]
	v_cvt_pk_bf16_f32 v88, v88, v89
	v_mul_f32_e32 v89, 0xbfb8aa3b, v84
	v_pk_mul_f32 v[90:91], v[92:93], v[90:91]
	v_exp_f32_e32 v92, v89
	v_mul_f32_e32 v89, 0xbfb8aa3b, v85
	v_exp_f32_e32 v93, v89
	v_cvt_pk_bf16_f32 v89, v90, v91
	v_add_f32_e32 v90, 1.0, v92
	v_mul_f32_e32 v92, 0xbfb8aa3b, v86
	v_add_f32_e32 v91, 1.0, v93
	v_mul_f32_e32 v93, 0xbfb8aa3b, v87
	v_exp_f32_e32 v92, v92
	v_exp_f32_e32 v93, v93
	v_rcp_f32_e32 v90, v90
	v_rcp_f32_e32 v91, v91
	v_add_f32_e32 v92, 1.0, v92
	v_add_f32_e32 v93, 1.0, v93
	v_rcp_f32_e32 v92, v92
	v_rcp_f32_e32 v93, v93
	v_pk_mul_f32 v[84:85], v[84:85], v[90:91]
	v_cvt_pk_bf16_f32 v107, v96, v97
	v_pk_mul_f32 v[80:81], v[84:85], v[80:81]
	v_mul_f32_e32 v84, 0xbfb8aa3b, v78
	v_cvt_pk_bf16_f32 v90, v80, v81
	v_pk_mul_f32 v[80:81], v[86:87], v[92:93]
	v_mul_f32_e32 v85, 0xbfb8aa3b, v79
	v_pk_mul_f32 v[80:81], v[80:81], v[82:83]
	v_mul_f32_e32 v82, 0xbfb8aa3b, v76
	v_mul_f32_e32 v83, 0xbfb8aa3b, v77
	v_exp_f32_e32 v82, v82
	v_exp_f32_e32 v83, v83
	v_exp_f32_e32 v84, v84
	v_exp_f32_e32 v85, v85
	v_add_f32_e32 v82, 1.0, v82
	v_add_f32_e32 v83, 1.0, v83
	v_rcp_f32_e32 v82, v82
	v_rcp_f32_e32 v83, v83
	v_add_f32_e32 v84, 1.0, v84
	v_add_f32_e32 v85, 1.0, v85
	v_rcp_f32_e32 v84, v84
	v_rcp_f32_e32 v85, v85
	v_pk_mul_f32 v[76:77], v[76:77], v[82:83]
	v_or_b32_e32 v96, 32, v154
	v_pk_mul_f32 v[72:73], v[76:77], v[72:73]
	v_pk_mul_f32 v[76:77], v[78:79], v[84:85]
	v_cvt_pk_bf16_f32 v72, v72, v73
	v_mul_f32_e32 v73, 0xbfb8aa3b, v68
	v_pk_mul_f32 v[74:75], v[76:77], v[74:75]
	v_exp_f32_e32 v76, v73
	v_mul_f32_e32 v73, 0xbfb8aa3b, v69
	v_exp_f32_e32 v77, v73
	v_cvt_pk_bf16_f32 v73, v74, v75
	v_add_f32_e32 v74, 1.0, v76
	v_mul_f32_e32 v76, 0xbfb8aa3b, v70
	v_add_f32_e32 v75, 1.0, v77
	v_mul_f32_e32 v77, 0xbfb8aa3b, v71
	v_exp_f32_e32 v76, v76
; __device__ __forceinline__ unsigned pk2(float lo, float hi) { const f32x2c v = {lo, hi}; const bf16x2c b = __builtin_convertvector(v, bf16x2c); return __builtin_bit_cast(unsigned, b); }
; __device__ __forceinline__ float silu_f(float x) { return x * fast_sigmoid(x); }
;     __device__ __forceinline__ void operator()(const f32x4 (&acc)[2][2][4][2], const pg8::Unit& u, int wr, int wc, int fr, int fq) const {
;         const int row0 = u.pm * 256 + wr * 64 + fr, col0 = u.pn * 128 + wc * 32 + 8 * fq;
; #pragma unroll
;         for (int ai = 0; ai < 2; ++ai)
; #pragma unroll
;             for (int m = 0; m < 4; ++m) {
;                 bf16_t* rowp = O + (size_t)(row0 + ai * 128 + m * 16) * ldc + col0;
;                 const f32x4 a0 = acc[ai][0][m][0], a1 = acc[ai][0][m][1], b0 = acc[ai][1][m][0], b1 = acc[ai][1][m][1];
;                 u32x4 w;
;                 w.x = pk2(silu_f(a0[0]) * b0[0], silu_f(a0[1]) * b0[1]); w.y = pk2(silu_f(a0[2]) * b0[2], silu_f(a0[3]) * b0[3]);
;                 w.z = pk2(silu_f(a1[0]) * b1[0], silu_f(a1[1]) * b1[1]); w.w = pk2(silu_f(a1[2]) * b1[2], silu_f(a1[3]) * b1[3]);
;                 *(u32x4*)rowp = w;
;             }
	v_exp_f32_e32 v77, v77
	v_rcp_f32_e32 v74, v74
	v_rcp_f32_e32 v75, v75
	v_add_f32_e32 v76, 1.0, v76
	v_add_f32_e32 v77, 1.0, v77
	v_rcp_f32_e32 v76, v76
	v_rcp_f32_e32 v77, v77
	v_pk_mul_f32 v[68:69], v[68:69], v[74:75]
	v_cvt_pk_bf16_f32 v91, v80, v81
	v_pk_mul_f32 v[64:65], v[68:69], v[64:65]
	v_mul_f32_e32 v68, 0xbfb8aa3b, v62
	v_cvt_pk_bf16_f32 v74, v64, v65
	v_pk_mul_f32 v[64:65], v[70:71], v[76:77]
	v_mul_f32_e32 v69, 0xbfb8aa3b, v63
	v_pk_mul_f32 v[64:65], v[64:65], v[66:67]
	v_mul_f32_e32 v66, 0xbfb8aa3b, v60
	v_mul_f32_e32 v67, 0xbfb8aa3b, v61
	v_exp_f32_e32 v66, v66
	v_exp_f32_e32 v67, v67
	v_exp_f32_e32 v68, v68
	v_exp_f32_e32 v69, v69
	v_add_f32_e32 v66, 1.0, v66
	v_add_f32_e32 v67, 1.0, v67
	v_rcp_f32_e32 v66, v66
	v_rcp_f32_e32 v67, v67
	v_add_f32_e32 v68, 1.0, v68
	v_add_f32_e32 v69, 1.0, v69
	v_rcp_f32_e32 v68, v68
	v_rcp_f32_e32 v69, v69
	v_pk_mul_f32 v[60:61], v[60:61], v[66:67]
	v_or_b32_e32 v80, 48, v154
	v_pk_mul_f32 v[56:57], v[60:61], v[56:57]
	v_pk_mul_f32 v[60:61], v[62:63], v[68:69]
	v_cvt_pk_bf16_f32 v56, v56, v57
	v_mul_f32_e32 v57, 0xbfb8aa3b, v52
	v_pk_mul_f32 v[58:59], v[60:61], v[58:59]
	v_exp_f32_e32 v60, v57
	v_mul_f32_e32 v57, 0xbfb8aa3b, v53
	v_exp_f32_e32 v61, v57
	v_cvt_pk_bf16_f32 v57, v58, v59
	v_add_f32_e32 v58, 1.0, v60
	v_mul_f32_e32 v60, 0xbfb8aa3b, v54
	v_add_f32_e32 v59, 1.0, v61
	v_mul_f32_e32 v61, 0xbfb8aa3b, v55
	v_exp_f32_e32 v60, v60
	v_exp_f32_e32 v61, v61
	v_rcp_f32_e32 v58, v58
	v_rcp_f32_e32 v59, v59
	v_add_f32_e32 v60, 1.0, v60
	v_add_f32_e32 v61, 1.0, v61
	v_rcp_f32_e32 v60, v60
	v_rcp_f32_e32 v61, v61
	v_pk_mul_f32 v[52:53], v[52:53], v[58:59]
	v_cvt_pk_bf16_f32 v75, v64, v65
	v_pk_mul_f32 v[48:49], v[52:53], v[48:49]
	v_mul_f32_e32 v52, 0xbfb8aa3b, v46
	v_cvt_pk_bf16_f32 v58, v48, v49
	v_pk_mul_f32 v[48:49], v[54:55], v[60:61]
	v_mul_f32_e32 v53, 0xbfb8aa3b, v47
	v_pk_mul_f32 v[48:49], v[48:49], v[50:51]
	v_mul_f32_e32 v50, 0xbfb8aa3b, v44
	v_mul_f32_e32 v51, 0xbfb8aa3b, v45
	v_exp_f32_e32 v50, v50
	v_exp_f32_e32 v51, v51
	v_exp_f32_e32 v52, v52
	v_exp_f32_e32 v53, v53
	v_add_f32_e32 v50, 1.0, v50
	v_add_f32_e32 v51, 1.0, v51
	v_rcp_f32_e32 v50, v50
	v_rcp_f32_e32 v51, v51
	v_add_f32_e32 v52, 1.0, v52
	v_add_f32_e32 v53, 1.0, v53
	v_rcp_f32_e32 v52, v52
	v_rcp_f32_e32 v53, v53
	v_pk_mul_f32 v[44:45], v[44:45], v[50:51]
	v_add_u32_e32 v64, 0x80, v154
	v_pk_mul_f32 v[40:41], v[44:45], v[40:41]
	v_pk_mul_f32 v[44:45], v[46:47], v[52:53]
	v_cvt_pk_bf16_f32 v40, v40, v41
	v_mul_f32_e32 v41, 0xbfb8aa3b, v36
	v_pk_mul_f32 v[42:43], v[44:45], v[42:43]
	v_exp_f32_e32 v44, v41
	v_mul_f32_e32 v41, 0xbfb8aa3b, v37
	v_exp_f32_e32 v45, v41
	v_cvt_pk_bf16_f32 v41, v42, v43
	v_add_f32_e32 v42, 1.0, v44
	v_mul_f32_e32 v44, 0xbfb8aa3b, v38
	v_add_f32_e32 v43, 1.0, v45
	v_mul_f32_e32 v45, 0xbfb8aa3b, v39
	v_exp_f32_e32 v44, v44
	v_exp_f32_e32 v45, v45
	v_rcp_f32_e32 v42, v42
	v_rcp_f32_e32 v43, v43
	v_add_f32_e32 v44, 1.0, v44
	v_add_f32_e32 v45, 1.0, v45
	v_rcp_f32_e32 v44, v44
	v_rcp_f32_e32 v45, v45
	v_pk_mul_f32 v[36:37], v[36:37], v[42:43]
	v_cvt_pk_bf16_f32 v59, v48, v49
	v_pk_mul_f32 v[32:33], v[36:37], v[32:33]
	v_mul_f32_e32 v36, 0xbfb8aa3b, v30
	v_cvt_pk_bf16_f32 v42, v32, v33
	v_pk_mul_f32 v[32:33], v[38:39], v[44:45]
	v_mul_f32_e32 v37, 0xbfb8aa3b, v31
	v_pk_mul_f32 v[32:33], v[32:33], v[34:35]
	v_mul_f32_e32 v34, 0xbfb8aa3b, v28
	v_mul_f32_e32 v35, 0xbfb8aa3b, v29
	v_exp_f32_e32 v34, v34
	v_exp_f32_e32 v35, v35
	v_exp_f32_e32 v36, v36
	v_exp_f32_e32 v37, v37
	v_add_f32_e32 v34, 1.0, v34
	v_add_f32_e32 v35, 1.0, v35
	v_rcp_f32_e32 v34, v34
	v_rcp_f32_e32 v35, v35
	v_add_f32_e32 v36, 1.0, v36
	v_add_f32_e32 v37, 1.0, v37
	v_rcp_f32_e32 v36, v36
	v_rcp_f32_e32 v37, v37
	v_pk_mul_f32 v[28:29], v[28:29], v[34:35]
	v_add_u32_e32 v48, 0x90, v154
; __device__ __forceinline__ unsigned pk2(float lo, float hi) { const f32x2c v = {lo, hi}; const bf16x2c b = __builtin_convertvector(v, bf16x2c); return __builtin_bit_cast(unsigned, b); }
; __device__ __forceinline__ float silu_f(float x) { return x * fast_sigmoid(x); }
; template <class Epi, class Sched, bool ALIGN_EPI = false, bool SP2 = false>
; __device__ __forceinline__ void gemm_phase(PG8_LAS unsigned char* lds, const Gemm g, const Sched& S, const Epi& E, const int wid) {
;     ...
;         if constexpr (!Epi::AFTER_DRAIN) { E(acc, cur, wr, wc, fr, fq); S.done(cur); }
;         if (!has_next) break;
;     __device__ __forceinline__ void operator()(const f32x4 (&acc)[2][2][4][2], const pg8::Unit& u, int wr, int wc, int fr, int fq) const {
;         const int row0 = u.pm * 256 + wr * 64 + fr, col0 = u.pn * 128 + wc * 32 + 8 * fq;
; #pragma unroll
;         for (int ai = 0; ai < 2; ++ai)
; #pragma unroll
;             for (int m = 0; m < 4; ++m) {
;                 bf16_t* rowp = O + (size_t)(row0 + ai * 128 + m * 16) * ldc + col0;
;                 const f32x4 a0 = acc[ai][0][m][0], a1 = acc[ai][0][m][1], b0 = acc[ai][1][m][0], b1 = acc[ai][1][m][1];
;                 u32x4 w;
;                 w.x = pk2(silu_f(a0[0]) * b0[0], silu_f(a0[1]) * b0[1]); w.y = pk2(silu_f(a0[2]) * b0[2], silu_f(a0[3]) * b0[3]);
;                 w.z = pk2(silu_f(a1[0]) * b1[0], silu_f(a1[1]) * b1[1]); w.w = pk2(silu_f(a1[2]) * b1[2], silu_f(a1[3]) * b1[3]);
;                 *(u32x4*)rowp = w;
;             }
	v_pk_mul_f32 v[24:25], v[28:29], v[24:25]
	v_pk_mul_f32 v[28:29], v[30:31], v[36:37]
	v_cvt_pk_bf16_f32 v24, v24, v25
	v_mul_f32_e32 v25, 0xbfb8aa3b, v20
	v_pk_mul_f32 v[26:27], v[28:29], v[26:27]
	v_exp_f32_e32 v28, v25
	v_mul_f32_e32 v25, 0xbfb8aa3b, v21
	v_exp_f32_e32 v29, v25
	v_cvt_pk_bf16_f32 v25, v26, v27
	v_add_f32_e32 v26, 1.0, v28
	v_mul_f32_e32 v28, 0xbfb8aa3b, v22
	v_add_f32_e32 v27, 1.0, v29
	v_mul_f32_e32 v29, 0xbfb8aa3b, v23
	v_exp_f32_e32 v28, v28
	v_exp_f32_e32 v29, v29
	v_rcp_f32_e32 v26, v26
	v_rcp_f32_e32 v27, v27
	v_add_f32_e32 v28, 1.0, v28
	v_add_f32_e32 v29, 1.0, v29
	v_rcp_f32_e32 v28, v28
	v_rcp_f32_e32 v29, v29
	v_pk_mul_f32 v[20:21], v[20:21], v[26:27]
	v_cvt_pk_bf16_f32 v43, v32, v33
	v_pk_mul_f32 v[16:17], v[20:21], v[16:17]
	v_mul_f32_e32 v20, 0xbfb8aa3b, v14
	v_cvt_pk_bf16_f32 v26, v16, v17
	v_pk_mul_f32 v[16:17], v[22:23], v[28:29]
	v_mul_f32_e32 v21, 0xbfb8aa3b, v15
	v_pk_mul_f32 v[16:17], v[16:17], v[18:19]
	v_mul_f32_e32 v18, 0xbfb8aa3b, v12
	v_mul_f32_e32 v19, 0xbfb8aa3b, v13
	v_exp_f32_e32 v18, v18
	v_exp_f32_e32 v19, v19
	v_exp_f32_e32 v20, v20
	v_exp_f32_e32 v21, v21
	v_add_f32_e32 v18, 1.0, v18
	v_add_f32_e32 v19, 1.0, v19
	v_rcp_f32_e32 v18, v18
	v_rcp_f32_e32 v19, v19
	v_add_f32_e32 v20, 1.0, v20
	v_add_f32_e32 v21, 1.0, v21
	v_rcp_f32_e32 v20, v20
	v_rcp_f32_e32 v21, v21
	v_pk_mul_f32 v[12:13], v[12:13], v[18:19]
	v_add_u32_e32 v32, 0xa0, v154
	v_pk_mul_f32 v[8:9], v[12:13], v[8:9]
	v_pk_mul_f32 v[12:13], v[14:15], v[20:21]
	v_cvt_pk_bf16_f32 v8, v8, v9
	v_mul_f32_e32 v9, 0xbfb8aa3b, v4
	v_pk_mul_f32 v[10:11], v[12:13], v[10:11]
	v_exp_f32_e32 v12, v9
	v_mul_f32_e32 v9, 0xbfb8aa3b, v5
	v_exp_f32_e32 v13, v9
	v_cvt_pk_bf16_f32 v9, v10, v11
	v_add_f32_e32 v10, 1.0, v12
	v_mul_f32_e32 v12, 0xbfb8aa3b, v6
	v_add_f32_e32 v11, 1.0, v13
	v_mul_f32_e32 v13, 0xbfb8aa3b, v7
	v_exp_f32_e32 v12, v12
	v_exp_f32_e32 v13, v13
	v_rcp_f32_e32 v10, v10
	v_rcp_f32_e32 v11, v11
	v_add_f32_e32 v12, 1.0, v12
	v_add_f32_e32 v13, 1.0, v13
	v_rcp_f32_e32 v12, v12
	v_rcp_f32_e32 v13, v13
	v_pk_mul_f32 v[4:5], v[4:5], v[10:11]
	v_cvt_pk_bf16_f32 v27, v16, v17
	v_pk_mul_f32 v[0:1], v[4:5], v[0:1]
	v_add_u32_e32 v16, 0xb0, v154
	v_cvt_pk_bf16_f32 v10, v0, v1
	v_pk_mul_f32 v[0:1], v[6:7], v[12:13]
	v_mad_i64_i32 v[156:157], s[22:23], v154, s44, v[146:147]
	v_lshlrev_b64 v[144:145], 1, v[144:145]
	v_mad_i64_i32 v[112:113], s[22:23], v112, s44, v[146:147]
	v_mad_i64_i32 v[96:97], s[22:23], v96, s44, v[146:147]
	v_mad_i64_i32 v[80:81], s[22:23], v80, s44, v[146:147]
	v_mad_i64_i32 v[64:65], s[22:23], v64, s44, v[146:147]
	v_mad_i64_i32 v[48:49], s[22:23], v48, s44, v[146:147]
	v_mad_i64_i32 v[32:33], s[22:23], v32, s44, v[146:147]
	v_mad_i64_i32 v[16:17], s[22:23], v16, s44, v[146:147]
	v_pk_mul_f32 v[0:1], v[0:1], v[2:3]
	v_lshl_add_u64 v[156:157], v[156:157], 0, v[144:145]
	v_lshl_add_u64 v[112:113], v[112:113], 0, v[144:145]
	v_lshl_add_u64 v[96:97], v[96:97], 0, v[144:145]
	v_lshl_add_u64 v[80:81], v[80:81], 0, v[144:145]
	v_lshl_add_u64 v[64:65], v[64:65], 0, v[144:145]
	v_lshl_add_u64 v[48:49], v[48:49], 0, v[144:145]
	v_lshl_add_u64 v[32:33], v[32:33], 0, v[144:145]
	v_lshl_add_u64 v[16:17], v[16:17], 0, v[144:145]
	v_cvt_pk_bf16_f32 v11, v0, v1
	s_andn2_b64 vcc, exec, s[6:7]
	s_mov_b64 s[6:7], -1
	global_store_dwordx4 v[156:157], v[120:123], off
	global_store_dwordx4 v[112:113], v[104:107], off
	global_store_dwordx4 v[96:97], v[88:91], off
	global_store_dwordx4 v[80:81], v[72:75], off
	global_store_dwordx4 v[64:65], v[56:59], off
	global_store_dwordx4 v[48:49], v[40:43], off
	global_store_dwordx4 v[32:33], v[24:27], off
	global_store_dwordx4 v[16:17], v[8:11], off
	s_cbranch_vccnz .LBB0_1307
	s_andn2_b64 vcc, exec, s[0:1]
	s_cbranch_vccnz .LBB0_1306
	s_barrier
	s_branch .LBB0_1306

; #define PG8_STAGE(bufoff, gbase, voff) do { _Pragma("unroll") for (int _i = 0; _i < 2; ++_i) \
;         __builtin_amdgcn_global_load_lds((const unsigned*)((const char*)(gbase) + (voff)[_i]), (PG8_LAS unsigned*)(lds + (bufoff) + ldsw + _i * 8192), 16, 0, 0); } while (0)
; #define PG8_WAIT_V(n) asm volatile("s_waitcnt vmcnt(" #n ")" ::: "memory")
; #define PG8_BAR __builtin_amdgcn_s_barrier()
; template <class Epi, class Sched, bool ALIGN_EPI = false, bool SP2 = false>
; __device__ __forceinline__ void gemm_phase(PG8_LAS unsigned char* lds, const Gemm g, const Sched& S, const Epi& E, const int wid) {
;     ...
;     for (int i = 0; i < 2; ++i) { int R, C; stage_rc(tid * 16 + i * 8192, R, C); const int Rb = Epi::PERM ? ((R & ~31) + perm32(R & 31)) : R;
;         voffA[i] = (unsigned)(R * K + C) * 2u; voffB[i] = (unsigned)(Rb * K + C) * 2u; }
;     const size_t kstep = (size_t)(BK * 2);
;     const size_t hstep = (size_t)HALF * K * 2;
;     const size_t tstep = 2 * hstep;
;     const unsigned ldsw = (unsigned)wid * 1024u;
;     const int aoff = lds_byte(wr * 64 + fr, fq * 8), boff = lds_byte(wc * 32 + fr, fq * 8);
;     ...
;     const char* cA = (const char*)g.A + (size_t)cur.pm * tstep; const char* cB = (const char*)g.Bt + (size_t)cur.pn * tstep;
;     S.a_ready(cur);
;     if constexpr (SP2) {
;         PG8_STAGE(PG8_SB(0, 0), cB, voffB); PG8_STAGE(PG8_SB(0, 1), cB + hstep, voffB); PG8_STAGE(PG8_SA(0, 0), cA, voffA); PG8_STAGE(PG8_SA(0, 1), cA + hstep, voffA);
;         if (wr == 1) PG8_BAR;
;         PG8_WAIT_V(2); PG8_BAR;
;         PG8_STAGE(PG8_SB(1, 0), cB + kstep, voffB); PG8_STAGE(PG8_SA(1, 0), cA + kstep, voffA); PG8_STAGE(PG8_SB(1, 1), cB + hstep + kstep, voffB);
.LBB0_1377:
	v_lshl_add_u32 v0, v8, 4, s33
	v_ashrrev_i32_e32 v1, 31, v0
	v_lshrrev_b32_e32 v1, 22, v1
	v_add_u32_e32 v1, v0, v1
	v_ashrrev_i32_e32 v9, 10, v1
	v_mul_i32_i24_e32 v1, 0x400, v9
	v_sub_u32_e32 v1, v0, v1
	v_lshrrev_b32_e32 v2, 4, v1
	v_bitop3_b32 v1, v2, v1, 32 bitop3:0x6c
	v_ashrrev_i32_e32 v3, 31, v1
	v_lshrrev_b32_e32 v3, 26, v3
	v_lshlrev_b32_e32 v2, 3, v9
	v_add_u32_e32 v3, v1, v3
	v_and_b32_e32 v2, -16, v2
	v_ashrrev_i32_e32 v11, 6, v3
	v_and_b32_e32 v3, 0xc0, v3
	v_add_u32_e32 v2, v11, v2
	v_lshlrev_b32_e32 v4, 5, v9
	v_sub_u32_e32 v1, v1, v3
	v_mov_b32_e32 v3, 1
	v_and_b32_e32 v10, 32, v4
	v_ashrrev_i16_sdwa v1, v3, sext(v1) dst_sel:DWORD dst_unused:UNUSED_PAD src0_sel:DWORD src1_sel:BYTE_0
	v_lshlrev_b32_e32 v4, 1, v2
	v_lshrrev_b32_e32 v5, 2, v2
	v_and_b32_e32 v6, 3, v11
	s_mov_b32 s3, 0xffffe0
	v_bfe_i32 v12, v1, 0, 16
	v_and_b32_e32 v4, 24, v4
	v_and_b32_e32 v5, 4, v5
	v_and_or_b32 v6, v2, s3, v6
	s_movk_i32 s0, 0xb00
	v_add_u32_e32 v1, v10, v12
	v_or3_b32 v4, v6, v5, v4
	v_mul_lo_u32 v2, v2, s0
	v_add_lshl_u32 v128, v1, v2, 1
	v_mul_u32_u24_e32 v2, 0xb00, v4
	v_add_u32_e32 v0, 0x2000, v0
	v_add_lshl_u32 v130, v2, v1, 1
	v_ashrrev_i32_e32 v1, 31, v0
	v_lshrrev_b32_e32 v1, 22, v1
	v_add_u32_e32 v1, v0, v1
	v_ashrrev_i32_e32 v13, 10, v1
	v_mul_i32_i24_e32 v1, 0x400, v13
	v_sub_u32_e32 v0, v0, v1
	v_lshrrev_b32_e32 v1, 4, v0
	v_bitop3_b32 v0, v1, v0, 32 bitop3:0x6c
	s_add_u32 s29, s92, 0x1c80000
	v_ashrrev_i32_e32 v2, 31, v0
	s_addc_u32 s30, s93, 0
	v_lshrrev_b32_e32 v2, 26, v2
	s_add_i32 s1, s2, s1
	v_lshlrev_b32_e32 v1, 3, v13
	v_add_u32_e32 v2, v0, v2
	s_ashr_i32 s2, s1, 31
	v_and_b32_e32 v1, -16, v1
	v_ashrrev_i32_e32 v14, 6, v2
	v_lshlrev_b32_e32 v4, 5, v13
	s_lshr_b32 s2, s2, 28
	v_add_u32_e32 v1, v14, v1
	v_and_b32_e32 v15, 32, v4
	v_and_b32_e32 v4, 3, v14
	s_add_i32 s2, s1, s2
	v_and_or_b32 v4, v1, s3, v4
	s_ashr_i32 s3, s2, 4
	s_and_b32 s2, s2, 0xfff0
	s_sub_i32 s2, s1, s2
	s_bfe_i32 s1, s2, 0x80000
	s_bfe_u32 s1, s1, 0x2000d
	s_add_i32 s4, s2, s1
	v_and_b32_e32 v2, 0xffc0, v2
	s_bfe_i32 s1, s4, 0x80000
	s_and_b32 s4, s4, 0xfc
	v_sub_u32_e32 v0, v0, v2
	s_sub_i32 s2, s2, s4
	v_lshrrev_b16_e32 v2, 7, v0
	s_lshl_b32 s3, s3, 2
	s_sext_i32_i16 s5, s1
	s_sext_i32_i8 s2, s2
	v_and_b32_e32 v2, 1, v2
	s_add_i32 s47, s3, s2
	s_ashr_i32 s2, s5, 2
	v_add_u16_e32 v0, v0, v2
	s_lshr_b32 s1, s5, 2
	s_mul_hi_i32 s3, s2, 0x160000
	s_mul_i32 s2, s2, 0x160000
	v_ashrrev_i16_sdwa v0, v3, sext(v0) dst_sel:DWORD dst_unused:UNUSED_PAD src0_sel:DWORD src1_sel:BYTE_0
	v_lshlrev_b32_e32 v2, 1, v1
	v_lshrrev_b32_e32 v3, 2, v1
	s_add_u32 s22, s29, s2
	v_bfe_i32 v16, v0, 0, 16
	v_and_b32_e32 v2, 24, v2
	v_and_b32_e32 v3, 4, v3
	s_addc_u32 s23, s30, s3
	s_add_i32 s31, s33, 0
	v_add_u32_e32 v0, v15, v16
	v_or3_b32 v2, v4, v3, v2
	v_mul_lo_u32 v1, v1, s0
	s_add_i32 m0, s31, 0x10000
	v_add_lshl_u32 v132, v0, v1, 1
	v_mul_u32_u24_e32 v1, 0xb00, v2
	global_load_lds_dwordx4 v130, s[22:23]
	s_add_i32 m0, s31, 0x12000
	v_add_lshl_u32 v134, v1, v0, 1
	s_add_u32 s2, s22, 0xb0000
	global_load_lds_dwordx4 v134, s[22:23]
	s_addc_u32 s3, s23, 0
	s_add_i32 m0, s31, 0x14000
	s_mul_i32 s6, s47, 0x160000
	global_load_lds_dwordx4 v130, s[2:3]
	s_add_i32 m0, s31, 0x16000
	s_mul_hi_i32 s4, s47, 0x160000
	s_add_u32 s20, s96, s6
	s_addc_u32 s21, s97, s4
	s_add_u32 s20, s20, 0xd000000
	s_addc_u32 s21, s21, 0
	s_add_i32 s34, s31, 0x2000
	global_load_lds_dwordx4 v134, s[2:3]
	s_mov_b32 m0, s31
	s_add_u32 s2, s20, 0xb0000
	global_load_lds_dwordx4 v128, s[20:21]
	s_mov_b32 m0, s34
	s_addc_u32 s3, s21, 0
	s_add_i32 s35, s31, 0x4000
	global_load_lds_dwordx4 v132, s[20:21]
	s_mov_b32 m0, s35
	s_add_i32 s36, s31, 0x6000
	global_load_lds_dwordx4 v128, s[2:3]
	s_mov_b32 m0, s36
	v_mov_b32_e32 v131, 0
	global_load_lds_dwordx4 v132, s[2:3]
	v_readlane_b32 s4, v244, 18
	v_mov_b32_e32 v135, v131
	v_mov_b32_e32 v129, v131
	v_mov_b32_e32 v133, v131
	s_cmp_eq_u32 s4, 1
	s_mov_b32 s37, 0
	v_lshl_add_u64 v[4:5], s[22:23], 0, v[130:131]
	v_lshl_add_u64 v[2:3], s[22:23], 0, v[134:135]
	s_mov_b64 s[2:3], 0xb0000
	v_lshl_add_u64 v[0:1], s[20:21], 0, v[128:129]
	s_cselect_b64 s[6:7], -1, 0
	s_cmp_lg_u32 s4, 1
	v_lshl_add_u64 v[6:7], s[20:21], 0, v[132:133]
	s_cbranch_scc1 .LBB0_1379
	s_barrier

; template <class Epi, class Sched, bool ALIGN_EPI = false, bool SP2 = false>
; __device__ __forceinline__ void gemm_phase(PG8_LAS unsigned char* lds, const Gemm g, const Sched& S, const Epi& E, const int wid) {
;     ...
;         const bool has_next = S.next(ui + 1, nxt);
;         const char* nA = has_next ? (const char*)g.A + (size_t)nxt.pm * tstep : cA; const char* nB = has_next ? (const char*)g.Bt + (size_t)nxt.pn * tstep : cB;
;         for (int t = 0; t < nt; t += 2) {
;             const bool last = (t == nt - 2);
;             const char* a1 = cA + (size_t)(t + 1) * kstep;
;             const char* a2 = last ? nA : cA + (size_t)(t + 2) * kstep; const char* b2 = last ? nB : cB + (size_t)(t + 2) * kstep;
;             const char* a3 = a2 + kstep; const char* b3 = b2 + kstep;
;             if (last && has_next) S.a_ready(nxt);
.LBB0_1388:
	s_nop 0
	v_cndmask_b32_e64 v0, 0, 1, s[4:5]
	v_cmp_ne_u32_e64 s[0:1], 1, v0
	s_andn2_b64 vcc, exec, s[4:5]
	s_mov_b64 s[4:5], s[20:21]
	s_cbranch_vccnz .LBB0_1390
	s_mul_i32 s4, s46, 0x160000
	s_mul_hi_i32 s5, s46, 0x160000
	s_add_u32 s4, s96, s4
	s_addc_u32 s5, s97, s5
	s_add_u32 s4, s4, 0xd000000
	s_addc_u32 s5, s5, 0
